# P5: only the first of the four waves of a row group runs the router softmax and stores the affinities (the others repeated identical work)
# speedup vs baseline: 1.0112x; 1.0112x over previous
.Lp5n_loop:
	s_and_b32 s51, s98, 1
	s_and_b32 s101, s98, 6
	s_lshl_b32 s61, s100, 3
	s_add_i32 s61, s61, s101
	s_lshl_b32 s62, s61, 4
	s_lshl_b32 s101, s94, 8
	s_add_i32 s62, s62, s101
	v_or_b32_e32 v130, s62, v120
	s_lshl_b32 s50, s51, 4
	v_add_u32_e32 v16, s50, v130
	v_ashrrev_i32_e32 v17, 31, v16
	v_lshlrev_b64 v[16:17], 12, v[16:17]
	v_mov_b32_e32 v135, 0
	v_lshl_add_u64 v[118:119], v[96:97], 0, v[16:17]
	v_mov_b32_e32 v16, 0
	v_mov_b32_e32 v17, v135
	v_mov_b32_e32 v18, v135
	v_mov_b32_e32 v19, v135
	s_lshl_b32 s0, s99, 10
	s_mov_b32 s1, 0
	s_lshl_b32 s101, s99, 13
	v_add_u32_e32 v84, s101, v129
	v_lshl_add_u64 v[236:237], v[118:119], 0, s[0:1]
	global_load_dwordx4 v[148:151], v[236:237], off offset:16
	global_load_dwordx4 v[152:155], v[236:237], off
	global_load_dwordx4 v[156:159], v[236:237], off offset:144
	global_load_dwordx4 v[160:163], v[236:237], off offset:128
	global_load_dwordx4 v[164:167], v[236:237], off offset:272
	global_load_dwordx4 v[168:171], v[236:237], off offset:256
	global_load_dwordx4 v[172:175], v[236:237], off offset:400
	global_load_dwordx4 v[176:179], v[236:237], off offset:384
	global_load_dwordx4 v[196:199], v[236:237], off offset:528
	global_load_dwordx4 v[200:203], v[236:237], off offset:512
	global_load_dwordx4 v[204:207], v[236:237], off offset:656
	global_load_dwordx4 v[208:211], v[236:237], off offset:640
	global_load_dwordx4 v[212:215], v[236:237], off offset:768
	global_load_dwordx4 v[216:219], v[236:237], off offset:784
	global_load_dwordx4 v[220:223], v[236:237], off offset:912
	global_load_dwordx4 v[224:227], v[236:237], off offset:896
	v_add_u32_e32 v238, s50, v130
	v_ashrrev_i32_e32 v239, 31, v238
	v_lshlrev_b64 v[238:239], 11, v[238:239]
	v_lshl_add_u64 v[238:239], s[78:79], 0, v[238:239]
	v_lshl_add_u64 v[238:239], v[238:239], 0, v[240:241]
	s_waitcnt vmcnt(0)
	v_mov_b64_e32 v[80:81], v[148:149]
	v_mov_b64_e32 v[82:83], v[150:151]
	v_mov_b64_e32 v[136:137], v[152:153]
	v_mov_b64_e32 v[138:139], v[154:155]
	v_mov_b64_e32 v[68:69], v[156:157]
	v_mov_b64_e32 v[70:71], v[158:159]
	v_mov_b64_e32 v[72:73], v[160:161]
	v_mov_b64_e32 v[74:75], v[162:163]
	v_mov_b64_e32 v[60:61], v[164:165]
	v_mov_b64_e32 v[62:63], v[166:167]
	v_mov_b64_e32 v[64:65], v[168:169]
	v_mov_b64_e32 v[66:67], v[170:171]
	v_mov_b64_e32 v[52:53], v[172:173]
	v_mov_b64_e32 v[54:55], v[174:175]
	v_mov_b64_e32 v[56:57], v[176:177]
	v_mov_b64_e32 v[58:59], v[178:179]
	v_mov_b64_e32 v[44:45], v[196:197]
	v_mov_b64_e32 v[46:47], v[198:199]
	v_mov_b64_e32 v[48:49], v[200:201]
	v_mov_b64_e32 v[50:51], v[202:203]
	v_mov_b64_e32 v[36:37], v[204:205]
	v_mov_b64_e32 v[38:39], v[206:207]
	v_mov_b64_e32 v[40:41], v[208:209]
	v_mov_b64_e32 v[42:43], v[210:211]
	v_mov_b64_e32 v[32:33], v[212:213]
	v_mov_b64_e32 v[34:35], v[214:215]
	v_mov_b64_e32 v[28:29], v[216:217]
	v_mov_b64_e32 v[30:31], v[218:219]
	v_mov_b64_e32 v[20:21], v[220:221]
	v_mov_b64_e32 v[22:23], v[222:223]
	v_mov_b64_e32 v[24:25], v[224:225]
	v_mov_b64_e32 v[26:27], v[226:227]
	v_cvt_pk_bf16_f32 v78, v80, v81
	v_fmac_f32_e32 v135, v136, v136
	v_fmac_f32_e32 v135, v137, v137
	v_fmac_f32_e32 v135, v138, v138
	v_cvt_pk_bf16_f32 v76, v136, v137
	v_cvt_pk_bf16_f32 v77, v138, v139
	v_fmac_f32_e32 v135, v139, v139
	v_lshlrev_b32_e32 v140, 16, v76
	v_and_b32_e32 v141, 0xffff0000, v76
	v_lshlrev_b32_e32 v142, 16, v77
	v_and_b32_e32 v143, 0xffff0000, v77
	v_lshlrev_b32_e32 v144, 16, v78
	v_and_b32_e32 v145, 0xffff0000, v78
	v_sub_f32_e32 v140, v136, v140
	v_sub_f32_e32 v141, v137, v141
	v_sub_f32_e32 v142, v138, v142
	v_sub_f32_e32 v143, v139, v143
	v_fmac_f32_e32 v135, v80, v80
	v_sub_f32_e32 v144, v80, v144
	v_sub_f32_e32 v145, v81, v145
	v_fmac_f32_e32 v135, v81, v81
	v_cvt_pk_bf16_f32 v80, v140, v141
	v_cvt_pk_bf16_f32 v81, v142, v143
	ds_read_b128 v[136:139], v84
	ds_read_b128 v[140:143], v84 offset:32768
	v_cvt_pk_bf16_f32 v79, v82, v83
	v_fmac_f32_e32 v135, v82, v82
	s_waitcnt lgkmcnt(1)
	v_mfma_f32_16x16x32_bf16 v[16:19], v[76:79], v[136:139], v[16:19]
	v_lshlrev_b32_e32 v146, 16, v79
	v_and_b32_e32 v147, 0xffff0000, v79
	v_sub_f32_e32 v146, v82, v146
	v_sub_f32_e32 v147, v83, v147
	v_fmac_f32_e32 v135, v83, v83
	v_cvt_pk_bf16_f32 v82, v144, v145
	v_cvt_pk_bf16_f32 v83, v146, v147
	v_fmac_f32_e32 v135, v72, v72
	v_mfma_f32_16x16x32_bf16 v[16:19], v[80:83], v[136:139], v[16:19]
	v_fmac_f32_e32 v135, v73, v73
	v_fmac_f32_e32 v135, v74, v74
	v_fmac_f32_e32 v135, v75, v75
	s_waitcnt lgkmcnt(0)
	v_mfma_f32_16x16x32_bf16 v[16:19], v[76:79], v[140:143], v[16:19]
	v_cvt_pk_bf16_f32 v76, v72, v73
	v_cvt_pk_bf16_f32 v77, v74, v75
	v_cvt_pk_bf16_f32 v78, v68, v69
	v_fmac_f32_e32 v135, v68, v68
	v_lshlrev_b32_e32 v80, 16, v76
	v_and_b32_e32 v81, 0xffff0000, v76
	v_lshlrev_b32_e32 v82, 16, v77
	v_and_b32_e32 v83, 0xffff0000, v77
	v_lshlrev_b32_e32 v136, 16, v78
	v_and_b32_e32 v137, 0xffff0000, v78
	v_sub_f32_e32 v80, v72, v80
	v_sub_f32_e32 v81, v73, v81
	v_sub_f32_e32 v82, v74, v82
	v_sub_f32_e32 v83, v75, v83
	v_sub_f32_e32 v136, v68, v136
	v_sub_f32_e32 v137, v69, v137
	v_fmac_f32_e32 v135, v69, v69
	v_cvt_pk_bf16_f32 v68, v80, v81
	v_cvt_pk_bf16_f32 v69, v82, v83
	ds_read_b128 v[72:75], v84 offset:1024
	ds_read_b128 v[80:83], v84 offset:33792
	v_cvt_pk_bf16_f32 v79, v70, v71
	v_fmac_f32_e32 v135, v70, v70
	s_waitcnt lgkmcnt(1)
	v_mfma_f32_16x16x32_bf16 v[16:19], v[76:79], v[72:75], v[16:19]
	v_lshlrev_b32_e32 v138, 16, v79
	v_and_b32_e32 v139, 0xffff0000, v79
	v_fmac_f32_e32 v135, v71, v71
	v_sub_f32_e32 v138, v70, v138
	v_sub_f32_e32 v139, v71, v139
	v_cvt_pk_bf16_f32 v70, v136, v137
	v_cvt_pk_bf16_f32 v71, v138, v139
	v_fmac_f32_e32 v135, v64, v64
	v_mfma_f32_16x16x32_bf16 v[16:19], v[68:71], v[72:75], v[16:19]
	v_fmac_f32_e32 v135, v65, v65
	v_fmac_f32_e32 v135, v66, v66
	v_cvt_pk_bf16_f32 v68, v64, v65
	v_cvt_pk_bf16_f32 v69, v66, v67
	v_fmac_f32_e32 v135, v67, v67
	v_lshlrev_b32_e32 v72, 16, v68
	v_and_b32_e32 v73, 0xffff0000, v68
	v_lshlrev_b32_e32 v74, 16, v69
	v_and_b32_e32 v75, 0xffff0000, v69
	s_waitcnt lgkmcnt(0)
	v_mfma_f32_16x16x32_bf16 v[16:19], v[76:79], v[80:83], v[16:19]
	v_cvt_pk_bf16_f32 v70, v60, v61
	v_sub_f32_e32 v72, v64, v72
	v_lshlrev_b32_e32 v76, 16, v70
	v_and_b32_e32 v77, 0xffff0000, v70
	v_sub_f32_e32 v73, v65, v73
	v_sub_f32_e32 v74, v66, v74
	v_sub_f32_e32 v75, v67, v75
	v_fmac_f32_e32 v135, v60, v60
	v_sub_f32_e32 v76, v60, v76
	v_sub_f32_e32 v77, v61, v77
	v_fmac_f32_e32 v135, v61, v61
	v_cvt_pk_bf16_f32 v60, v72, v73
	v_cvt_pk_bf16_f32 v61, v74, v75
	ds_read_b128 v[64:67], v84 offset:2048
	ds_read_b128 v[72:75], v84 offset:34816
	v_cvt_pk_bf16_f32 v71, v62, v63
	v_fmac_f32_e32 v135, v62, v62
	s_waitcnt lgkmcnt(1)
	v_mfma_f32_16x16x32_bf16 v[16:19], v[68:71], v[64:67], v[16:19]
	v_lshlrev_b32_e32 v78, 16, v71
	v_and_b32_e32 v79, 0xffff0000, v71
	v_fmac_f32_e32 v135, v63, v63
	v_sub_f32_e32 v78, v62, v78
	v_sub_f32_e32 v79, v63, v79
	v_cvt_pk_bf16_f32 v62, v76, v77
	v_cvt_pk_bf16_f32 v63, v78, v79
	v_fmac_f32_e32 v135, v56, v56
	v_mfma_f32_16x16x32_bf16 v[16:19], v[60:63], v[64:67], v[16:19]
	v_fmac_f32_e32 v135, v57, v57
	v_fmac_f32_e32 v135, v58, v58
	v_cvt_pk_bf16_f32 v60, v56, v57
	v_cvt_pk_bf16_f32 v61, v58, v59
	v_fmac_f32_e32 v135, v59, v59
	v_lshlrev_b32_e32 v64, 16, v60
	v_and_b32_e32 v65, 0xffff0000, v60
	v_lshlrev_b32_e32 v66, 16, v61
	v_and_b32_e32 v67, 0xffff0000, v61
	s_waitcnt lgkmcnt(0)
	v_mfma_f32_16x16x32_bf16 v[16:19], v[68:71], v[72:75], v[16:19]
	v_cvt_pk_bf16_f32 v62, v52, v53
	v_sub_f32_e32 v64, v56, v64
	v_lshlrev_b32_e32 v68, 16, v62
	v_and_b32_e32 v69, 0xffff0000, v62
	v_sub_f32_e32 v65, v57, v65
	v_sub_f32_e32 v66, v58, v66
	v_sub_f32_e32 v67, v59, v67
	v_fmac_f32_e32 v135, v52, v52
	v_sub_f32_e32 v68, v52, v68
	v_sub_f32_e32 v69, v53, v69
	v_fmac_f32_e32 v135, v53, v53
	v_cvt_pk_bf16_f32 v52, v64, v65
	v_cvt_pk_bf16_f32 v53, v66, v67
	ds_read_b128 v[56:59], v84 offset:3072
	ds_read_b128 v[64:67], v84 offset:35840
	v_cvt_pk_bf16_f32 v63, v54, v55
	v_fmac_f32_e32 v135, v54, v54
	s_waitcnt lgkmcnt(1)
	v_mfma_f32_16x16x32_bf16 v[16:19], v[60:63], v[56:59], v[16:19]
	v_lshlrev_b32_e32 v70, 16, v63
	v_and_b32_e32 v71, 0xffff0000, v63
	v_fmac_f32_e32 v135, v55, v55
	v_sub_f32_e32 v70, v54, v70
	v_sub_f32_e32 v71, v55, v71
	v_cvt_pk_bf16_f32 v54, v68, v69
	v_cvt_pk_bf16_f32 v55, v70, v71
	v_fmac_f32_e32 v135, v48, v48
	v_mfma_f32_16x16x32_bf16 v[16:19], v[52:55], v[56:59], v[16:19]
	v_fmac_f32_e32 v135, v49, v49
	v_fmac_f32_e32 v135, v50, v50
	v_cvt_pk_bf16_f32 v52, v48, v49
	v_cvt_pk_bf16_f32 v53, v50, v51
	v_fmac_f32_e32 v135, v51, v51
	v_lshlrev_b32_e32 v56, 16, v52
	v_and_b32_e32 v57, 0xffff0000, v52
	v_lshlrev_b32_e32 v58, 16, v53
	v_and_b32_e32 v59, 0xffff0000, v53
	s_waitcnt lgkmcnt(0)
	v_mfma_f32_16x16x32_bf16 v[16:19], v[60:63], v[64:67], v[16:19]
	v_cvt_pk_bf16_f32 v54, v44, v45
	v_sub_f32_e32 v56, v48, v56
	v_lshlrev_b32_e32 v60, 16, v54
	v_and_b32_e32 v61, 0xffff0000, v54
	v_sub_f32_e32 v57, v49, v57
	v_sub_f32_e32 v58, v50, v58
	v_sub_f32_e32 v59, v51, v59
	v_fmac_f32_e32 v135, v44, v44
	v_sub_f32_e32 v60, v44, v60
	v_sub_f32_e32 v61, v45, v61
	v_fmac_f32_e32 v135, v45, v45
	v_cvt_pk_bf16_f32 v44, v56, v57
	v_cvt_pk_bf16_f32 v45, v58, v59
	ds_read_b128 v[48:51], v84 offset:4096
	ds_read_b128 v[56:59], v84 offset:36864
	v_cvt_pk_bf16_f32 v55, v46, v47
	v_fmac_f32_e32 v135, v46, v46
	s_waitcnt lgkmcnt(1)
	v_mfma_f32_16x16x32_bf16 v[16:19], v[52:55], v[48:51], v[16:19]
	v_lshlrev_b32_e32 v62, 16, v55
	v_and_b32_e32 v63, 0xffff0000, v55
	v_fmac_f32_e32 v135, v47, v47
	v_sub_f32_e32 v62, v46, v62
	v_sub_f32_e32 v63, v47, v63
	v_cvt_pk_bf16_f32 v46, v60, v61
	v_cvt_pk_bf16_f32 v47, v62, v63
	v_fmac_f32_e32 v135, v40, v40
	v_mfma_f32_16x16x32_bf16 v[16:19], v[44:47], v[48:51], v[16:19]
	v_fmac_f32_e32 v135, v41, v41
	v_fmac_f32_e32 v135, v42, v42
	v_cvt_pk_bf16_f32 v44, v40, v41
	v_cvt_pk_bf16_f32 v45, v42, v43
	v_fmac_f32_e32 v135, v43, v43
	v_lshlrev_b32_e32 v48, 16, v44
	v_and_b32_e32 v49, 0xffff0000, v44
	v_lshlrev_b32_e32 v50, 16, v45
	v_and_b32_e32 v51, 0xffff0000, v45
	s_waitcnt lgkmcnt(0)
	v_mfma_f32_16x16x32_bf16 v[16:19], v[52:55], v[56:59], v[16:19]
	v_cvt_pk_bf16_f32 v46, v36, v37
	v_sub_f32_e32 v48, v40, v48
	v_lshlrev_b32_e32 v52, 16, v46
	v_and_b32_e32 v53, 0xffff0000, v46
	v_sub_f32_e32 v49, v41, v49
	v_sub_f32_e32 v50, v42, v50
	v_sub_f32_e32 v51, v43, v51
	v_fmac_f32_e32 v135, v36, v36
	v_sub_f32_e32 v52, v36, v52
	v_sub_f32_e32 v53, v37, v53
	v_fmac_f32_e32 v135, v37, v37
	v_cvt_pk_bf16_f32 v36, v48, v49
	v_cvt_pk_bf16_f32 v37, v50, v51
	ds_read_b128 v[40:43], v84 offset:5120
	ds_read_b128 v[48:51], v84 offset:37888
	v_cvt_pk_bf16_f32 v47, v38, v39
	v_fmac_f32_e32 v135, v38, v38
	s_waitcnt lgkmcnt(1)
	v_mfma_f32_16x16x32_bf16 v[16:19], v[44:47], v[40:43], v[16:19]
	v_lshlrev_b32_e32 v54, 16, v47
	v_and_b32_e32 v55, 0xffff0000, v47
	v_sub_f32_e32 v54, v38, v54
	v_sub_f32_e32 v55, v39, v55
	v_fmac_f32_e32 v135, v39, v39
	v_cvt_pk_bf16_f32 v38, v52, v53
	v_cvt_pk_bf16_f32 v39, v54, v55
	v_fmac_f32_e32 v135, v32, v32
	v_mfma_f32_16x16x32_bf16 v[16:19], v[36:39], v[40:43], v[16:19]
	v_mov_b32_e32 v36, v28
	v_mov_b32_e32 v37, v35
	v_pk_mul_f32 v[42:43], v[30:31], v[30:31]
	v_fmac_f32_e32 v135, v33, v33
	v_pk_mul_f32 v[40:41], v[36:37], v[36:37]
	v_cvt_pk_bf16_f32 v36, v32, v33
	v_fmac_f32_e32 v135, v34, v34
	v_lshlrev_b32_e32 v43, 16, v36
	s_waitcnt lgkmcnt(0)
	v_mfma_f32_16x16x32_bf16 v[16:19], v[44:47], v[48:51], v[16:19]
	v_mul_f32_e64 v44, v28, v28
	v_mul_f32_e64 v45, v29, v29
	v_sub_f32_e32 v43, v32, v43
	v_add_f32_e32 v32, v41, v135
	v_cvt_pk_bf16_f32 v37, v34, v35
	v_cvt_pk_bf16_f32 v39, v30, v31
	v_and_b32_e32 v44, 0xffff0000, v36
	v_lshlrev_b32_e32 v46, 16, v37
	v_and_b32_e32 v47, 0xffff0000, v37
	v_and_b32_e32 v51, 0xffff0000, v39
	v_add_f32_e32 v32, v40, v32
	v_cvt_pk_bf16_f32 v38, v28, v29
	v_lshlrev_b32_e32 v50, 16, v39
	v_lshlrev_b32_e32 v48, 16, v38
	v_sub_f32_e32 v44, v33, v44
	v_sub_f32_e32 v46, v34, v46
	v_sub_f32_e32 v35, v35, v47
	v_sub_f32_e32 v47, v31, v51
	v_add_f32_e32 v32, v45, v32
	v_sub_f32_e32 v28, v28, v48
	v_sub_f32_e32 v30, v30, v50
	v_add_f32_e32 v48, v42, v32
	v_cvt_pk_bf16_f32 v32, v43, v44
	v_cvt_pk_bf16_f32 v33, v46, v35
	v_cvt_pk_bf16_f32 v35, v30, v47
	ds_read_b128 v[40:43], v84 offset:6144
	ds_read_b128 v[44:47], v84 offset:38912
	s_waitcnt lgkmcnt(1)
	v_mfma_f32_16x16x32_bf16 v[16:19], v[36:39], v[40:43], v[16:19]
	v_and_b32_e32 v49, 0xffff0000, v38
	v_sub_f32_e32 v29, v29, v49
	v_cvt_pk_bf16_f32 v34, v28, v29
	v_mov_b32_e32 v30, v24
	v_mfma_f32_16x16x32_bf16 v[16:19], v[32:35], v[40:43], v[16:19]
	v_mul_f32_e64 v32, v30, v30
	v_mul_f32_e64 v33, v31, v31
	v_pk_mul_f32 v[34:35], v[26:27], v[26:27]
	v_mov_b32_e32 v28, v20
	v_mov_b32_e32 v29, v27
	s_waitcnt lgkmcnt(0)
	v_mfma_f32_16x16x32_bf16 v[16:19], v[36:39], v[44:47], v[16:19]
	v_add_f32_e32 v33, v33, v48
	v_pk_mul_f32 v[38:39], v[28:29], v[28:29]
	v_cvt_pk_bf16_f32 v28, v24, v25
	v_cvt_pk_bf16_f32 v30, v20, v21
	v_pk_mul_f32 v[36:37], v[24:25], v[24:25]
	v_lshlrev_b32_e32 v35, 16, v28
	v_lshlrev_b32_e32 v44, 16, v30
	v_pk_mul_f32 v[42:43], v[20:21], v[20:21]
	v_sub_f32_e32 v24, v24, v35
	v_sub_f32_e32 v35, v20, v44
	v_add_f32_e32 v20, v32, v33
	v_add_f32_e32 v20, v37, v20
	v_add_f32_e32 v20, v34, v20
	v_pk_mul_f32 v[40:41], v[22:23], v[22:23]
	v_add_f32_e32 v20, v39, v20
	v_cvt_pk_bf16_f32 v29, v26, v27
	v_and_b32_e32 v36, 0xffff0000, v28
	v_lshlrev_b32_e32 v41, 16, v29
	v_and_b32_e32 v42, 0xffff0000, v29
	v_add_f32_e32 v20, v38, v20
	v_cvt_pk_bf16_f32 v31, v22, v23
	v_and_b32_e32 v45, 0xffff0000, v30
	v_lshlrev_b32_e32 v46, 16, v31
	v_sub_f32_e32 v25, v25, v36
	v_sub_f32_e32 v26, v26, v41
	v_sub_f32_e32 v27, v27, v42
	v_add_f32_e32 v20, v43, v20
	v_sub_f32_e32 v36, v21, v45
	v_sub_f32_e32 v41, v22, v46
	v_add_f32_e32 v135, v40, v20
	v_cvt_pk_bf16_f32 v20, v24, v25
	v_cvt_pk_bf16_f32 v21, v26, v27
	v_cvt_pk_bf16_f32 v22, v35, v36
	ds_read_b128 v[24:27], v84 offset:7168
	ds_read_b128 v[32:35], v84 offset:39936
	s_waitcnt lgkmcnt(1)
	v_mfma_f32_16x16x32_bf16 v[16:19], v[28:31], v[24:27], v[16:19]
	v_and_b32_e32 v47, 0xffff0000, v31
	v_sub_f32_e32 v42, v23, v47
	v_fmac_f32_e32 v135, v23, v23
	v_cvt_pk_bf16_f32 v23, v41, v42
	v_add_u32_e32 v84, 0x2000, v84
	v_mfma_f32_16x16x32_bf16 v[16:19], v[20:23], v[24:27], v[16:19]
	s_waitcnt lgkmcnt(0)
	v_mfma_f32_16x16x32_bf16 v[16:19], v[28:31], v[32:35], v[16:19]
	s_nop 7
	s_nop 7
	ds_write_b128 v231, v[16:19]
	ds_write_b32 v232, v135
	s_waitcnt lgkmcnt(0)
	s_barrier
	ds_read_b128 v[16:19], v233
	ds_read_b128 v[20:23], v233 offset:1280
	ds_read_b128 v[24:27], v233 offset:2560
	ds_read_b128 v[28:31], v233 offset:3840
	ds_read_b32 v135, v234
	ds_read_b32 v32, v234 offset:1280
	ds_read_b32 v33, v234 offset:2560
	ds_read_b32 v34, v234 offset:3840
	s_waitcnt lgkmcnt(0)
	v_pk_add_f32 v[16:17], v[16:17], v[20:21]
	v_pk_add_f32 v[18:19], v[18:19], v[22:23]
	v_pk_add_f32 v[16:17], v[16:17], v[24:25]
	v_pk_add_f32 v[18:19], v[18:19], v[26:27]
	v_pk_add_f32 v[16:17], v[16:17], v[28:29]
	v_pk_add_f32 v[18:19], v[18:19], v[30:31]
	v_add_f32_e32 v135, v135, v32
	v_add_f32_e32 v135, v135, v33
	v_add_f32_e32 v135, v135, v34
	v_and_b32_e32 v24, 64, v133
	v_xor_b32_e32 v20, 16, v133
	v_add_u32_e32 v21, 64, v24
	v_cmp_lt_i32_e32 vcc, v20, v21
	v_xor_b32_e32 v22, 32, v133
	s_mov_b32 s0, 0x800000
	v_cndmask_b32_e32 v20, v133, v20, vcc
	v_lshlrev_b32_e32 v20, 2, v20
	ds_bpermute_b32 v20, v20, v135
	v_cmp_lt_i32_e32 vcc, v22, v21
	v_or_b32_e32 v25, v24, v122
	v_lshlrev_b32_e32 v25, 2, v25
	v_cndmask_b32_e32 v22, v133, v22, vcc
	s_waitcnt lgkmcnt(0)
	v_add_f32_e32 v20, v135, v20
	v_lshlrev_b32_e32 v22, 2, v22
	ds_bpermute_b32 v22, v22, v20
	v_xor_b32_e32 v23, 1, v133
	v_or_b32_e32 v28, v24, v123
	s_add_i32 s84, s62, s50
	s_mov_b32 s85, -4
	s_waitcnt lgkmcnt(0)
	v_add_f32_e32 v20, v20, v22
	v_fmamk_f32 v20, v20, 0x3a800000, v132
	v_mul_f32_e32 v22, 0x4b800000, v20
	v_cmp_gt_f32_e32 vcc, s0, v20
	s_or_b32 s0, s51, s61
	s_lshl_b32 s0, s0, 4
	v_cndmask_b32_e32 v20, v20, v22, vcc
	v_rsq_f32_e32 v20, v20
	v_xor_b32_e32 v22, 2, v133
	s_add_i32 s0, s0, s33
	s_and_b32 s0, s0, 0xff0
	v_mul_f32_e32 v26, 0x45800000, v20
	v_cndmask_b32_e32 v64, v20, v26, vcc
	s_cmp_lg_u32 s99, 0
	s_cbranch_scc1 .Lp5n_nosm
	ds_bpermute_b32 v20, v25, v64
	v_cmp_lt_i32_e32 vcc, v23, v21
	v_xor_b32_e32 v25, 4, v133
	v_or_b32_e32 v30, s0, v122
	v_cndmask_b32_e32 v23, v133, v23, vcc
	v_lshlrev_b32_e32 v26, 2, v23
	s_waitcnt lgkmcnt(0)
	v_fma_f32 v16, v16, v20, v99
	ds_bpermute_b32 v20, v26, v16
	v_cmp_lt_i32_e32 vcc, v22, v21
	v_xor_b32_e32 v23, 8, v133
	v_lshlrev_b32_e32 v84, 2, v30
	v_cndmask_b32_e32 v22, v133, v22, vcc
	s_waitcnt lgkmcnt(0)
	v_max_f32_e32 v20, v20, v20
	v_lshlrev_b32_e32 v27, 2, v22
	v_max_f32_e32 v20, v16, v20
	ds_bpermute_b32 v22, v27, v20
	v_cmp_lt_i32_e32 vcc, v25, v21
	s_waitcnt lgkmcnt(0)
	v_max_f32_e32 v22, v22, v22
	v_cndmask_b32_e32 v25, v133, v25, vcc
	v_lshlrev_b32_e32 v29, 2, v25
	v_max_f32_e32 v20, v20, v22
	ds_bpermute_b32 v22, v29, v20
	v_lshlrev_b32_e32 v25, 2, v28
	ds_bpermute_b32 v25, v25, v64
	v_cmp_lt_i32_e32 vcc, v23, v21
	s_waitcnt lgkmcnt(0)
	v_fma_f32 v17, v17, v25, v99
	v_cndmask_b32_e32 v21, v133, v23, vcc
	v_lshlrev_b32_e32 v28, 2, v21
	v_max_f32_e32 v21, v22, v22
	v_max_f32_e32 v20, v20, v21
	ds_bpermute_b32 v22, v28, v20
	ds_bpermute_b32 v21, v26, v17
	s_waitcnt lgkmcnt(1)
	v_max_f32_e32 v22, v22, v22
	s_waitcnt lgkmcnt(0)
	v_max_f32_e32 v21, v21, v21
	v_max_f32_e32 v20, v20, v22
	v_sub_f32_e32 v16, v16, v20
	v_max_f32_e32 v20, v17, v21
	ds_bpermute_b32 v21, v27, v20
	v_mul_f32_e32 v22, 0x3fb8aa3b, v16
	v_fma_f32 v23, v16, s91, -v22
	v_rndne_f32_e32 v25, v22
	v_fmac_f32_e32 v23, 0x32a5705f, v16
	s_waitcnt lgkmcnt(0)
	v_max_f32_e32 v21, v21, v21
	v_max_f32_e32 v20, v20, v21
	ds_bpermute_b32 v21, v29, v20
	v_sub_f32_e32 v22, v22, v25
	v_add_f32_e32 v22, v22, v23
	v_exp_f32_e32 v22, v22
	v_cvt_i32_f32_e32 v23, v25
	s_waitcnt lgkmcnt(0)
	v_max_f32_e32 v21, v21, v21
	v_max_f32_e32 v20, v20, v21
	ds_bpermute_b32 v21, v28, v20
	v_ldexp_f32 v22, v22, v23
	v_cmp_ngt_f32_e32 vcc, s92, v16
	s_waitcnt lgkmcnt(0)
	v_max_f32_e32 v21, v21, v21
	v_max_f32_e32 v20, v20, v21
	v_sub_f32_e32 v17, v17, v20
	v_mul_f32_e32 v20, 0x3fb8aa3b, v17
	v_fma_f32 v21, v17, s91, -v20
	v_rndne_f32_e32 v23, v20
	v_fmac_f32_e32 v21, 0x32a5705f, v17
	v_sub_f32_e32 v20, v20, v23
	v_add_f32_e32 v20, v20, v21
	v_exp_f32_e32 v21, v20
	v_cvt_i32_f32_e32 v23, v23
	v_cndmask_b32_e32 v22, 0, v22, vcc
	v_cmp_nlt_f32_e32 vcc, s93, v16
	v_ldexp_f32 v21, v21, v23
	s_nop 0
	v_cndmask_b32_e32 v16, v134, v22, vcc
	v_cmp_ngt_f32_e32 vcc, s92, v17
	ds_bpermute_b32 v20, v26, v16
	s_nop 0
	v_cndmask_b32_e32 v21, 0, v21, vcc
	v_cmp_nlt_f32_e32 vcc, s93, v17
	s_nop 1
	v_cndmask_b32_e32 v17, v134, v21, vcc
	ds_bpermute_b32 v21, v26, v17
	s_waitcnt lgkmcnt(0)
	v_pk_add_f32 v[20:21], v[16:17], v[20:21]
	ds_bpermute_b32 v22, v27, v20
	ds_bpermute_b32 v23, v27, v21
	s_waitcnt lgkmcnt(0)
	v_pk_add_f32 v[20:21], v[20:21], v[22:23]
	v_or_b32_e32 v22, v24, v124
	v_lshlrev_b32_e32 v22, 2, v22
	ds_bpermute_b32 v25, v22, v64
	ds_bpermute_b32 v22, v29, v20
	ds_bpermute_b32 v23, v29, v21
	v_or_b32_e32 v24, v24, v125
	v_lshlrev_b32_e32 v24, 2, v24
	s_waitcnt lgkmcnt(2)
	v_fma_f32 v18, v18, v25, v99
	ds_bpermute_b32 v25, v26, v18
	s_waitcnt lgkmcnt(1)
	v_pk_add_f32 v[20:21], v[20:21], v[22:23]
	ds_bpermute_b32 v22, v28, v20
	ds_bpermute_b32 v23, v28, v21
	ds_bpermute_b32 v24, v24, v64
	s_waitcnt lgkmcnt(3)
	v_max_f32_e32 v25, v25, v25
	v_max_f32_e32 v25, v18, v25
	ds_bpermute_b32 v31, v27, v25
	s_waitcnt lgkmcnt(2)
	v_pk_add_f32 v[20:21], v[20:21], v[22:23]
	s_waitcnt lgkmcnt(1)
	v_fma_f32 v19, v19, v24, v99
	v_div_scale_f32 v32, s[0:1], v21, v21, v17
	s_waitcnt lgkmcnt(0)
	v_max_f32_e32 v22, v31, v31
	v_max_f32_e32 v25, v25, v22
	v_rcp_f32_e32 v33, v32
	ds_bpermute_b32 v31, v29, v25
	ds_bpermute_b32 v24, v26, v19
	v_lshl_add_u64 v[22:23], v[116:117], 0, v[84:85]
	v_fma_f32 v30, -v32, v33, 1.0
	v_fmac_f32_e32 v33, v30, v33
	s_waitcnt lgkmcnt(1)
	v_max_f32_e32 v30, v31, v31
	v_max_f32_e32 v25, v25, v30
	ds_bpermute_b32 v30, v28, v25
	s_waitcnt lgkmcnt(1)
	v_max_f32_e32 v24, v24, v24
	v_max_f32_e32 v24, v19, v24
	v_div_scale_f32 v31, vcc, v17, v21, v17
	s_waitcnt lgkmcnt(0)
	v_max_f32_e32 v30, v30, v30
	v_max_f32_e32 v25, v25, v30
	v_sub_f32_e32 v18, v18, v25
	ds_bpermute_b32 v25, v27, v24
	v_mul_f32_e32 v30, 0x3fb8aa3b, v18
	v_fma_f32 v35, v18, s91, -v30
	v_rndne_f32_e32 v36, v30
	v_fmac_f32_e32 v35, 0x32a5705f, v18
	s_waitcnt lgkmcnt(0)
	v_max_f32_e32 v25, v25, v25
	v_max_f32_e32 v24, v24, v25
	ds_bpermute_b32 v25, v29, v24
	v_sub_f32_e32 v30, v30, v36
	v_add_f32_e32 v30, v30, v35
	v_exp_f32_e32 v30, v30
	v_cvt_i32_f32_e32 v35, v36
	s_waitcnt lgkmcnt(0)
	v_max_f32_e32 v25, v25, v25
	v_max_f32_e32 v24, v24, v25
	ds_bpermute_b32 v25, v28, v24
	v_ldexp_f32 v30, v30, v35
	v_cmp_ngt_f32_e64 s[0:1], s92, v18
	v_mul_f32_e32 v34, v31, v33
	v_fma_f32 v36, -v32, v34, v31
	s_waitcnt lgkmcnt(0)
	v_max_f32_e32 v25, v25, v25
	v_max_f32_e32 v24, v24, v25
	v_sub_f32_e32 v19, v19, v24
	v_mul_f32_e32 v24, 0x3fb8aa3b, v19
	v_fma_f32 v25, v19, s91, -v24
	v_rndne_f32_e32 v35, v24
	v_fmac_f32_e32 v25, 0x32a5705f, v19
	v_sub_f32_e32 v24, v24, v35
	v_add_f32_e32 v24, v24, v25
	v_exp_f32_e32 v25, v24
	v_cvt_i32_f32_e32 v35, v35
	v_cndmask_b32_e64 v30, 0, v30, s[0:1]
	v_cmp_nlt_f32_e64 s[0:1], s93, v18
	v_fmac_f32_e32 v34, v36, v33
	v_ldexp_f32 v25, v25, v35
	v_cndmask_b32_e64 v18, v134, v30, s[0:1]
	v_cmp_ngt_f32_e64 s[0:1], s92, v19
	ds_bpermute_b32 v24, v26, v18
	s_nop 0
	v_cndmask_b32_e64 v25, 0, v25, s[0:1]
	v_cmp_nlt_f32_e64 s[0:1], s93, v19
	s_nop 1
	v_cndmask_b32_e64 v19, v134, v25, s[0:1]
	ds_bpermute_b32 v25, v26, v19
	v_fma_f32 v26, -v32, v34, v31
	v_div_fmas_f32 v30, v26, v33, v34
	v_div_fixup_f32 v17, v30, v21, v17
	v_div_scale_f32 v21, s[0:1], v20, v20, v16
	s_waitcnt lgkmcnt(0)
	v_pk_add_f32 v[24:25], v[18:19], v[24:25]
	ds_bpermute_b32 v26, v27, v24
	ds_bpermute_b32 v27, v27, v25
	v_rcp_f32_e32 v30, v21
	s_waitcnt lgkmcnt(0)
	v_pk_add_f32 v[24:25], v[24:25], v[26:27]
	ds_bpermute_b32 v26, v29, v24
	ds_bpermute_b32 v27, v29, v25
	v_fma_f32 v29, -v21, v30, 1.0
	v_fmac_f32_e32 v30, v29, v30
	v_div_scale_f32 v29, vcc, v16, v20, v16
	s_waitcnt lgkmcnt(0)
	v_pk_add_f32 v[24:25], v[24:25], v[26:27]
	ds_bpermute_b32 v26, v28, v24
	ds_bpermute_b32 v27, v28, v25
	v_mul_f32_e32 v28, v29, v30
	v_fma_f32 v31, -v21, v28, v29
	v_fmac_f32_e32 v28, v31, v30
	v_fma_f32 v21, -v21, v28, v29
	s_waitcnt lgkmcnt(0)
	v_pk_add_f32 v[24:25], v[24:25], v[26:27]
	v_div_fmas_f32 v21, v21, v30, v28
	v_div_scale_f32 v26, s[0:1], v25, v25, v19
	v_rcp_f32_e32 v27, v26
	v_div_fixup_f32 v16, v21, v20, v16
	v_fma_f32 v20, -v26, v27, 1.0
	v_fmac_f32_e32 v27, v20, v27
	v_div_scale_f32 v20, vcc, v19, v25, v19
	v_mul_f32_e32 v21, v20, v27
	v_fma_f32 v28, -v26, v21, v20
	v_fmac_f32_e32 v21, v28, v27
	v_fma_f32 v20, -v26, v21, v20
	v_div_scale_f32 v26, s[0:1], v24, v24, v18
	v_rcp_f32_e32 v28, v26
	v_div_fmas_f32 v20, v20, v27, v21
	v_div_fixup_f32 v19, v20, v25, v19
	v_fma_f32 v20, -v26, v28, 1.0
	v_fmac_f32_e32 v28, v20, v28
	v_div_scale_f32 v20, vcc, v18, v24, v18
	v_mul_f32_e32 v21, v20, v28
	v_fma_f32 v25, -v26, v21, v20
	v_fmac_f32_e32 v21, v25, v28
	v_fma_f32 v20, -v26, v21, v20
	v_div_fmas_f32 v20, v20, v28, v21
	v_div_fixup_f32 v18, v20, v24, v18
	global_store_dwordx4 v[22:23], v[16:19], off
	s_nop 1
	v_lshlrev_b32_e32 v16, 2, v133
	v_and_b32_e32 v65, 0x100, v16
.Lp5n_nosm:
	ds_read_b128 v[242:245], v230 offset:0
	ds_read_b128 v[246:249], v230 offset:16
	ds_read_b128 v[250:253], v230 offset:4096
	ds_read_b128 v[180:183], v230 offset:4112
	s_waitcnt lgkmcnt(0)
	v_pk_mul_f32 v[184:185], v[152:153], v[64:65] op_sel_hi:[1,0]
	v_pk_mul_f32 v[186:187], v[154:155], v[64:65] op_sel_hi:[1,0]
	v_pk_mul_f32 v[188:189], v[148:149], v[64:65] op_sel_hi:[1,0]
	v_pk_mul_f32 v[190:191], v[150:151], v[64:65] op_sel_hi:[1,0]
	v_pk_fma_f32 v[184:185], v[242:243], v[184:185], v[250:251]
	v_pk_fma_f32 v[186:187], v[244:245], v[186:187], v[252:253]
	v_pk_fma_f32 v[188:189], v[246:247], v[188:189], v[180:181]
	v_pk_fma_f32 v[190:191], v[248:249], v[190:191], v[182:183]
	v_cvt_pk_bf16_f32 v184, v184, v185
	v_cvt_pk_bf16_f32 v185, v186, v187
	v_cvt_pk_bf16_f32 v186, v188, v189
	v_cvt_pk_bf16_f32 v187, v190, v191
	global_store_dwordx4 v[238:239], v[184:187], off offset:0
	ds_read_b128 v[242:245], v230 offset:128
	ds_read_b128 v[246:249], v230 offset:144
	ds_read_b128 v[250:253], v230 offset:4224
	ds_read_b128 v[180:183], v230 offset:4240
	s_waitcnt lgkmcnt(0)
	v_pk_mul_f32 v[184:185], v[160:161], v[64:65] op_sel_hi:[1,0]
	v_pk_mul_f32 v[186:187], v[162:163], v[64:65] op_sel_hi:[1,0]
	v_pk_mul_f32 v[188:189], v[156:157], v[64:65] op_sel_hi:[1,0]
	v_pk_mul_f32 v[190:191], v[158:159], v[64:65] op_sel_hi:[1,0]
	v_pk_fma_f32 v[184:185], v[242:243], v[184:185], v[250:251]
	v_pk_fma_f32 v[186:187], v[244:245], v[186:187], v[252:253]
	v_pk_fma_f32 v[188:189], v[246:247], v[188:189], v[180:181]
	v_pk_fma_f32 v[190:191], v[248:249], v[190:191], v[182:183]
	v_cvt_pk_bf16_f32 v184, v184, v185
	v_cvt_pk_bf16_f32 v185, v186, v187
	v_cvt_pk_bf16_f32 v186, v188, v189
	v_cvt_pk_bf16_f32 v187, v190, v191
	global_store_dwordx4 v[238:239], v[184:187], off offset:64
	ds_read_b128 v[242:245], v230 offset:256
	ds_read_b128 v[246:249], v230 offset:272
	ds_read_b128 v[250:253], v230 offset:4352
	ds_read_b128 v[180:183], v230 offset:4368
	s_waitcnt lgkmcnt(0)
	v_pk_mul_f32 v[184:185], v[168:169], v[64:65] op_sel_hi:[1,0]
	v_pk_mul_f32 v[186:187], v[170:171], v[64:65] op_sel_hi:[1,0]
	v_pk_mul_f32 v[188:189], v[164:165], v[64:65] op_sel_hi:[1,0]
	v_pk_mul_f32 v[190:191], v[166:167], v[64:65] op_sel_hi:[1,0]
	v_pk_fma_f32 v[184:185], v[242:243], v[184:185], v[250:251]
	v_pk_fma_f32 v[186:187], v[244:245], v[186:187], v[252:253]
	v_pk_fma_f32 v[188:189], v[246:247], v[188:189], v[180:181]
	v_pk_fma_f32 v[190:191], v[248:249], v[190:191], v[182:183]
	v_cvt_pk_bf16_f32 v184, v184, v185
	v_cvt_pk_bf16_f32 v185, v186, v187
	v_cvt_pk_bf16_f32 v186, v188, v189
	v_cvt_pk_bf16_f32 v187, v190, v191
	global_store_dwordx4 v[238:239], v[184:187], off offset:128
	ds_read_b128 v[242:245], v230 offset:384
	ds_read_b128 v[246:249], v230 offset:400
	ds_read_b128 v[250:253], v230 offset:4480
	ds_read_b128 v[180:183], v230 offset:4496
	s_waitcnt lgkmcnt(0)
	v_pk_mul_f32 v[184:185], v[176:177], v[64:65] op_sel_hi:[1,0]
	v_pk_mul_f32 v[186:187], v[178:179], v[64:65] op_sel_hi:[1,0]
	v_pk_mul_f32 v[188:189], v[172:173], v[64:65] op_sel_hi:[1,0]
	v_pk_mul_f32 v[190:191], v[174:175], v[64:65] op_sel_hi:[1,0]
	v_pk_fma_f32 v[184:185], v[242:243], v[184:185], v[250:251]
	v_pk_fma_f32 v[186:187], v[244:245], v[186:187], v[252:253]
	v_pk_fma_f32 v[188:189], v[246:247], v[188:189], v[180:181]
	v_pk_fma_f32 v[190:191], v[248:249], v[190:191], v[182:183]
	v_cvt_pk_bf16_f32 v184, v184, v185
	v_cvt_pk_bf16_f32 v185, v186, v187
	v_cvt_pk_bf16_f32 v186, v188, v189
	v_cvt_pk_bf16_f32 v187, v190, v191
	global_store_dwordx4 v[238:239], v[184:187], off offset:192
	ds_read_b128 v[242:245], v230 offset:512
	ds_read_b128 v[246:249], v230 offset:528
	ds_read_b128 v[250:253], v230 offset:4608
	ds_read_b128 v[180:183], v230 offset:4624
	s_waitcnt lgkmcnt(0)
	v_pk_mul_f32 v[184:185], v[200:201], v[64:65] op_sel_hi:[1,0]
	v_pk_mul_f32 v[186:187], v[202:203], v[64:65] op_sel_hi:[1,0]
	v_pk_mul_f32 v[188:189], v[196:197], v[64:65] op_sel_hi:[1,0]
	v_pk_mul_f32 v[190:191], v[198:199], v[64:65] op_sel_hi:[1,0]
	v_pk_fma_f32 v[184:185], v[242:243], v[184:185], v[250:251]
	v_pk_fma_f32 v[186:187], v[244:245], v[186:187], v[252:253]
	v_pk_fma_f32 v[188:189], v[246:247], v[188:189], v[180:181]
	v_pk_fma_f32 v[190:191], v[248:249], v[190:191], v[182:183]
	v_cvt_pk_bf16_f32 v184, v184, v185
	v_cvt_pk_bf16_f32 v185, v186, v187
	v_cvt_pk_bf16_f32 v186, v188, v189
	v_cvt_pk_bf16_f32 v187, v190, v191
	global_store_dwordx4 v[238:239], v[184:187], off offset:256
	ds_read_b128 v[242:245], v230 offset:640
	ds_read_b128 v[246:249], v230 offset:656
	ds_read_b128 v[250:253], v230 offset:4736
	ds_read_b128 v[180:183], v230 offset:4752
	s_waitcnt lgkmcnt(0)
	v_pk_mul_f32 v[184:185], v[208:209], v[64:65] op_sel_hi:[1,0]
	v_pk_mul_f32 v[186:187], v[210:211], v[64:65] op_sel_hi:[1,0]
	v_pk_mul_f32 v[188:189], v[204:205], v[64:65] op_sel_hi:[1,0]
	v_pk_mul_f32 v[190:191], v[206:207], v[64:65] op_sel_hi:[1,0]
	v_pk_fma_f32 v[184:185], v[242:243], v[184:185], v[250:251]
	v_pk_fma_f32 v[186:187], v[244:245], v[186:187], v[252:253]
	v_pk_fma_f32 v[188:189], v[246:247], v[188:189], v[180:181]
	v_pk_fma_f32 v[190:191], v[248:249], v[190:191], v[182:183]
	v_cvt_pk_bf16_f32 v184, v184, v185
	v_cvt_pk_bf16_f32 v185, v186, v187
	v_cvt_pk_bf16_f32 v186, v188, v189
	v_cvt_pk_bf16_f32 v187, v190, v191
	global_store_dwordx4 v[238:239], v[184:187], off offset:320
	ds_read_b128 v[242:245], v230 offset:768
	ds_read_b128 v[246:249], v230 offset:784
	ds_read_b128 v[250:253], v230 offset:4864
	ds_read_b128 v[180:183], v230 offset:4880
	s_waitcnt lgkmcnt(0)
	v_pk_mul_f32 v[184:185], v[212:213], v[64:65] op_sel_hi:[1,0]
	v_pk_mul_f32 v[186:187], v[214:215], v[64:65] op_sel_hi:[1,0]
	v_pk_mul_f32 v[188:189], v[216:217], v[64:65] op_sel_hi:[1,0]
	v_pk_mul_f32 v[190:191], v[218:219], v[64:65] op_sel_hi:[1,0]
	v_pk_fma_f32 v[184:185], v[242:243], v[184:185], v[250:251]
	v_pk_fma_f32 v[186:187], v[244:245], v[186:187], v[252:253]
	v_pk_fma_f32 v[188:189], v[246:247], v[188:189], v[180:181]
	v_pk_fma_f32 v[190:191], v[248:249], v[190:191], v[182:183]
	v_cvt_pk_bf16_f32 v184, v184, v185
	v_cvt_pk_bf16_f32 v185, v186, v187
	v_cvt_pk_bf16_f32 v186, v188, v189
	v_cvt_pk_bf16_f32 v187, v190, v191
	global_store_dwordx4 v[238:239], v[184:187], off offset:384
	ds_read_b128 v[242:245], v230 offset:896
	ds_read_b128 v[246:249], v230 offset:912
	ds_read_b128 v[250:253], v230 offset:4992
	ds_read_b128 v[180:183], v230 offset:5008
	s_waitcnt lgkmcnt(0)
	v_pk_mul_f32 v[184:185], v[224:225], v[64:65] op_sel_hi:[1,0]
	v_pk_mul_f32 v[186:187], v[226:227], v[64:65] op_sel_hi:[1,0]
	v_pk_mul_f32 v[188:189], v[220:221], v[64:65] op_sel_hi:[1,0]
	v_pk_mul_f32 v[190:191], v[222:223], v[64:65] op_sel_hi:[1,0]
	v_pk_fma_f32 v[184:185], v[242:243], v[184:185], v[250:251]
	v_pk_fma_f32 v[186:187], v[244:245], v[186:187], v[252:253]
	v_pk_fma_f32 v[188:189], v[246:247], v[188:189], v[180:181]
	v_pk_fma_f32 v[190:191], v[248:249], v[190:191], v[182:183]
	v_cvt_pk_bf16_f32 v184, v184, v185
	v_cvt_pk_bf16_f32 v185, v186, v187
	v_cvt_pk_bf16_f32 v186, v188, v189
	v_cvt_pk_bf16_f32 v187, v190, v191
	global_store_dwordx4 v[238:239], v[184:187], off offset:448
	v_xor_b32_e32 v231, 0x8000, v231
	v_xor_b32_e32 v232, 0x8000, v232
	v_xor_b32_e32 v233, 0x8000, v233
	v_xor_b32_e32 v234, 0x8000, v234
	s_add_i32 s98, s98, 1
	s_cmp_lt_u32 s98, 8
	s_cbranch_scc1 .Lp5n_loop
	s_lshl_b32 s61, s100, 2
	s_add_i32 s61, s61, s99
	s_lshl_b32 s61, s61, 1
	s_lshl_b32 s62, s61, 4
	s_lshl_b32 s101, s94, 8
	s_add_i32 s62, s62, s101
	v_or_b32_e32 v130, s62, v120
	s_add_i32 s94, s94, s82
	s_add_i32 s62, s62, s63
	s_cmpk_gt_i32 s94, 0xff
	v_add_u32_e32 v130, s63, v130
	s_cbranch_scc0 .LBB0_738
